# v18 plus SSD conv weight loads hoisted to loop top and DPP row-shift prefix scan replacing seven ds_bpermute round trips
# baseline (speedup 1.0000x reference)
; __device__ __forceinline__ void ssd_phase(const Frame& F, const Args& a, int z, int li, bf16* PROJ, const float* DT, bf16* dryXB) {
;     ...
;                 const bf16* src = PROJ + 2048 + chbase;
;                 u32x4 raw[11];
; #pragma unroll
;                 for (int i = 0; i < 11; ++i) {
;                     const int rr = 8 * wave - 3 + i;
;                     if (rr >= 0 || c > 0) raw[i] = *(const u32x4*)(src + (size_t)((long)rowc + rr) * LDP);
;     ...
;                     f32x4 wv[4], bvv;
; #pragma unroll
;                     for (int k = 0; k < 4; ++k) wv[k] = *(const f32x4*)(conv_w + k * 4096 + chbase + 4 * hb);
;                     bvv = *(const f32x4*)(conv_b + chbase + 4 * hb);
.LBB0_414:
	s_andn2_saveexec_b64 s[6:7], s[6:7]
	v_add_u32_e32 v110, s5, v209
	s_or_b64 exec, exec, s[6:7]
	v_ashrrev_i32_e32 v111, 31, v110
	v_lshl_add_u64 v[224:225], v[110:111], 1, s[30:31]
	s_add_i32 s16, s50, s54
	v_mad_u64_u32 v[78:79], s[14:15], s16, v229, v[224:225]
	s_add_i32 s14, s50, s78
	s_nop 0
	v_mad_u64_u32 v[80:81], s[14:15], s14, v229, v[224:225]
	s_add_i32 s14, s16, 4
	s_nop 0
	v_mad_u64_u32 v[86:87], s[14:15], s14, v229, v[224:225]
	s_add_i32 s14, s16, 5
	s_nop 0
	v_mad_u64_u32 v[88:89], s[14:15], s14, v229, v[224:225]
	s_add_i32 s14, s16, 6
	s_nop 0
	v_mad_u64_u32 v[90:91], s[14:15], s14, v229, v[224:225]
	s_add_i32 s14, s16, 7
	s_add_i32 s17, s50, s85
	v_mad_u64_u32 v[94:95], s[14:15], s14, v229, v[224:225]
	s_add_i32 s16, s16, 3
	global_load_dwordx4 v[82:85], v[78:79], off
	s_nop 0
	global_load_dwordx4 v[78:81], v[80:81], off
	s_nop 0
	global_load_dwordx4 v[90:93], v[90:91], off
	s_nop 0
	global_load_dwordx4 v[98:101], v[94:95], off
	s_nop 0
	global_load_dwordx4 v[94:97], v[86:87], off
	s_nop 0
	global_load_dwordx4 v[86:89], v[88:89], off
	v_mad_u64_u32 v[104:105], s[14:15], s17, v229, v[224:225]
	v_mad_u64_u32 v[102:103], s[14:15], s16, v229, v[224:225]
	global_load_dwordx4 v[106:109], v[104:105], off
	s_nop 0
	global_load_dwordx4 v[102:105], v[102:103], off
	v_lshlrev_b64 v[234:235], 2, v[110:111]
	v_lshl_add_u64 v[194:195], s[18:19], 0, v[234:235]
	v_lshl_add_u64 v[192:193], s[20:21], 0, v[234:235]
	s_movk_i32 s14, 0x4000
	v_add_co_u32_e32 v234, vcc, s14, v194
	global_load_dwordx4 v[136:139], v[194:195], off
	s_nop 0
	v_addc_co_u32_e32 v235, vcc, 0, v195, vcc
	global_load_dwordx4 v[132:135], v[234:235], off
	global_load_dwordx4 v[144:147], v[192:193], off
	v_add_co_u32_e32 v234, vcc, s84, v194
	s_mov_b32 s14, 0xc000
	s_nop 0
	v_addc_co_u32_e32 v235, vcc, 0, v195, vcc
	global_load_dwordx4 v[140:143], v[234:235], off
	v_add_co_u32_e32 v234, vcc, s14, v194
	s_nop 1
	v_addc_co_u32_e32 v235, vcc, 0, v195, vcc
	global_load_dwordx4 v[148:151], v[234:235], off
	v_add_u32_e32 v0, s73, v168
	s_movk_i32 s6, 0x100
	v_cmp_gt_i32_e64 s[6:7], s6, v0
	s_and_saveexec_b64 s[14:15], s[6:7]
	s_cbranch_execz .LBB0_420
	v_add_f32_e32 v234, v207, v169
	s_mov_b32 s16, 0x41a00000
	v_cmp_nlt_f32_e32 vcc, s16, v234
	s_and_saveexec_b64 s[16:17], vcc
	s_cbranch_execz .LBB0_419
; __device__ __forceinline__ float fexp2(float x) { return __builtin_amdgcn_exp2f(x); }
; __device__ __forceinline__ void ssd_phase(const Frame& F, const Args& a, int z, int li, bf16* PROJ, const float* DT, bf16* dryXB) {
;     ...
;             if (tid < 256) {
;                 const int hr = g * 4 + wave;
;                 const float raw = dt_pf + dtb_i;
;                 const float dt = raw > 20.f ? raw : log1pf(__expf(raw));
;                 const float am = am_i;
;                 float v = dt * am;
; #pragma unroll
;                 for (int o = 1; o < 64; o <<= 1) { const float n = __shfl_up(v, o); if (lane >= o) v += n; }
;                 const float last = __shfl(v, 63);
;                 dts[wave * 64 + lane] = dt; cums[wave * 64 + lane] = v; wins[wave * 64 + lane] = fexp2(last - v) * dt;
;             }
	v_mul_f32_e32 v234, 0x3fb8aa3b, v234
	v_exp_f32_e32 v250, v234
	s_mov_b32 s44, 0x3f2aaaab
	v_add_f32_e32 v236, 1.0, v250
	v_frexp_mant_f32_e32 v240, v236
	v_cvt_f64_f32_e32 v[234:235], v236
	v_frexp_exp_i32_f64_e32 v234, v[234:235]
	v_cmp_gt_f32_e32 vcc, s44, v240
	v_add_f32_e32 v237, -1.0, v236
	v_sub_f32_e32 v241, v237, v236
	v_subbrev_co_u32_e32 v244, vcc, 0, v234, vcc
	v_sub_u32_e32 v234, 0, v244
	v_sub_f32_e32 v237, v250, v237
	v_add_f32_e32 v241, 1.0, v241
	v_ldexp_f32 v235, v236, v234
	v_add_f32_e32 v237, v237, v241
	v_add_f32_e32 v236, -1.0, v235
	v_add_f32_e32 v240, 1.0, v235
	v_ldexp_f32 v234, v237, v234
	v_add_f32_e32 v237, 1.0, v236
	v_add_f32_e32 v241, -1.0, v240
	v_sub_f32_e32 v237, v235, v237
	v_sub_f32_e32 v235, v235, v241
	v_add_f32_e32 v237, v234, v237
	v_add_f32_e32 v234, v234, v235
	v_add_f32_e32 v245, v240, v234
	v_rcp_f32_e32 v247, v245
	v_sub_f32_e32 v235, v245, v240
	v_sub_f32_e32 v246, v234, v235
	v_add_f32_e32 v235, v236, v237
	v_mul_f32_e32 v249, v235, v247
	v_sub_f32_e32 v234, v235, v236
	v_mul_f32_e32 v236, v245, v249
	v_fma_f32 v240, v249, v245, -v236
	v_fmac_f32_e32 v240, v249, v246
	v_sub_f32_e32 v248, v237, v234
	v_add_f32_e32 v234, v236, v240
	v_sub_f32_e32 v237, v235, v234
	v_pk_add_f32 v[242:243], v[234:235], v[236:237] neg_lo:[0,1] neg_hi:[0,1]
	v_mov_b32_e32 v241, v234
	v_pk_add_f32 v[234:235], v[242:243], v[240:241] neg_lo:[0,1] neg_hi:[0,1]
	s_mov_b32 s44, 0x3f317218
	v_add_f32_e32 v235, v248, v235
	v_add_f32_e32 v234, v234, v235
	v_add_f32_e32 v235, v237, v234
	v_mul_f32_e32 v248, v247, v235
	v_mul_f32_e32 v236, v245, v248
	v_fma_f32 v240, v248, v245, -v236
	v_fmac_f32_e32 v240, v248, v246
	v_sub_f32_e32 v237, v237, v235
	v_add_f32_e32 v245, v234, v237
	v_add_f32_e32 v234, v236, v240
	v_sub_f32_e32 v237, v235, v234
	v_pk_add_f32 v[242:243], v[234:235], v[236:237] neg_lo:[0,1] neg_hi:[0,1]
	v_mov_b32_e32 v241, v234
	v_pk_add_f32 v[234:235], v[242:243], v[240:241] neg_lo:[0,1] neg_hi:[0,1]
	s_nop 0
	v_add_f32_e32 v235, v245, v235
	v_add_f32_e32 v234, v234, v235
	v_add_f32_e32 v235, v249, v248
	v_add_f32_e32 v234, v237, v234
	v_sub_f32_e32 v236, v235, v249
	v_mul_f32_e32 v234, v247, v234
	v_sub_f32_e32 v236, v248, v236
	v_add_f32_e32 v236, v236, v234
	v_add_f32_e32 v240, v235, v236
	v_mul_f32_e32 v241, v240, v240
	v_mov_b32_e32 v234, 0x3ecc95a3
	v_fmamk_f32 v234, v241, 0x3e9b6dac, v234
	v_fmaak_f32 v175, v241, v234, 0x3f2aaada
	v_cvt_f32_i32_e32 v234, v244
	v_sub_f32_e32 v235, v240, v235
	v_sub_f32_e32 v235, v236, v235
	v_ldexp_f32 v242, v235, 1
	v_mul_f32_e32 v235, v240, v241
	v_ldexp_f32 v237, v240, 1
	v_pk_mul_f32 v[240:241], v[234:235], v[174:175]
	s_nop 0
	v_fma_f32 v236, v234, s44, -v240
	v_fmac_f32_e32 v236, 0xb102e308, v234
	v_pk_add_f32 v[234:235], v[240:241], v[236:237]
	s_mov_b32 s44, 0x7f800000
	v_sub_f32_e32 v237, v235, v237
	v_sub_f32_e32 v237, v241, v237
	v_add_f32_e32 v243, v242, v237
	v_mov_b32_e32 v242, v240
	v_pk_add_f32 v[240:241], v[234:235], v[240:241] neg_lo:[0,1] neg_hi:[0,1]
	v_pk_add_f32 v[244:245], v[234:235], v[242:243]
	v_mov_b32_e32 v237, v234
	v_mov_b32_e32 v241, v245
	v_pk_add_f32 v[246:247], v[236:237], v[240:241] neg_lo:[0,1] neg_hi:[0,1]
	v_pk_add_f32 v[236:237], v[236:237], v[240:241]
	v_mov_b32_e32 v242, v243
	v_pk_add_f32 v[240:241], v[236:237], v[234:235] op_sel:[1,0] op_sel_hi:[0,1] neg_lo:[0,1] neg_hi:[0,1]
	v_pk_add_f32 v[248:249], v[244:245], v[240:241] op_sel_hi:[1,0] neg_lo:[0,1] neg_hi:[0,1]
	v_mov_b32_e32 v244, v245
	v_mov_b32_e32 v245, v237
	v_pk_mov_b32 v[240:241], v[234:235], v[240:241] op_sel:[1,0]
	v_mov_b32_e32 v243, v234
	v_pk_add_f32 v[240:241], v[244:245], v[240:241] neg_lo:[0,1] neg_hi:[0,1]
	v_mov_b32_e32 v248, v246
	v_pk_add_f32 v[234:235], v[242:243], v[240:241] neg_lo:[0,1] neg_hi:[0,1]
	v_mov_b32_e32 v247, v237
	v_pk_add_f32 v[240:241], v[248:249], v[234:235]
	v_cmp_neq_f32_e32 vcc, s44, v250
	v_pk_add_f32 v[242:243], v[240:241], v[240:241] op_sel:[0,1] op_sel_hi:[1,0]
	s_mov_b32 s44, 0x33800000
	v_pk_add_f32 v[236:237], v[236:237], v[242:243] op_sel:[1,0] op_sel_hi:[0,1]
	v_mov_b32_e32 v241, v236
	v_pk_add_f32 v[244:245], v[240:241], v[246:247] neg_lo:[0,1] neg_hi:[0,1]
	v_mov_b32_e32 v235, v242
	v_sub_f32_e32 v237, v240, v244
	v_pk_add_f32 v[234:235], v[234:235], v[244:245] neg_lo:[0,1] neg_hi:[0,1]
	v_sub_f32_e32 v237, v246, v237
	v_add_f32_e32 v234, v234, v237
	v_add_f32_e32 v234, v234, v235
	v_add_f32_e32 v234, v236, v234
	v_mov_b32_e32 v235, 0x7f800000
	v_cndmask_b32_e32 v234, v235, v234, vcc
	v_cmp_ngt_f32_e32 vcc, -1.0, v250
	v_mov_b32_e32 v235, 0x7fc00000
	s_nop 0
	v_cndmask_b32_e32 v234, v235, v234, vcc
	v_cmp_neq_f32_e32 vcc, -1.0, v250
	v_mov_b32_e32 v235, 0xff800000
	s_nop 0
	v_cndmask_b32_e32 v234, v235, v234, vcc
	v_cmp_lt_f32_e64 vcc, |v250|, s44
	s_nop 1
	v_cndmask_b32_e32 v234, v234, v250, vcc
.LBB0_419:
	s_or_b64 exec, exec, s[16:17]
	v_mul_f32_e32 v235, v208, v234
	v_lshl_add_u32 v0, v0, 2, 0
	v_add_u32_e32 v237, 0x1f000, v0
	ds_write_b32 v237, v234
	v_add_f32_dpp v235, v235, v235 row_shr:1 row_mask:0xf bank_mask:0xf bound_ctrl:0
	v_add_u32_e32 v237, 0x1f400, v0
	v_add_u32_e32 v0, 0x1f800, v0
	v_add_f32_dpp v235, v235, v235 row_shr:2 row_mask:0xf bank_mask:0xf bound_ctrl:0
	s_nop 1
	v_add_f32_dpp v235, v235, v235 row_shr:4 row_mask:0xf bank_mask:0xf bound_ctrl:0
	s_nop 1
	v_add_f32_dpp v235, v235, v235 row_shr:8 row_mask:0xf bank_mask:0xf bound_ctrl:0
	s_nop 1
	v_add_f32_dpp v235, v235, v235 row_bcast:15 row_mask:0xa bank_mask:0xf
	s_nop 1
	v_add_f32_dpp v235, v235, v235 row_bcast:31 row_mask:0xc bank_mask:0xf
	s_nop 1
	ds_write_b32 v237, v235
	v_readlane_b32 s16, v235, 63
	s_nop 1
	v_sub_f32_e32 v235, s16, v235
	v_exp_f32_e32 v235, v235
	s_nop 0
	v_mul_f32_e32 v234, v234, v235
	ds_write_b32 v0, v234

; __device__ __forceinline__ unsigned pk2(float lo, float hi) { f32x2_t v = {lo, hi}; bf16x2_t b = __builtin_convertvector(v, bf16x2_t); return __builtin_bit_cast(unsigned, b); }
; __device__ __forceinline__ float bflo(unsigned u) { return __uint_as_float(u << 16); }
; __device__ __forceinline__ float bfhi(unsigned u) { return __uint_as_float(u & 0xffff0000u); }
; __device__ __forceinline__ float silu_f(float v) { return v * frcp(1.0f + fexp2(-v * LOG2E)); }
; __device__ __forceinline__ void ssd_phase(const Frame& F, const Args& a, int z, int li, bf16* PROJ, const float* DT, bf16* dryXB) {
;     ...
;                 for (int hb = 0; hb < 2; ++hb) {
;                     f32x4 wv[4], bvv;
; #pragma unroll
;                     for (int k = 0; k < 4; ++k) wv[k] = *(const f32x4*)(conv_w + k * 4096 + chbase + 4 * hb);
;                     bvv = *(const f32x4*)(conv_b + chbase + 4 * hb);
;                     unsigned pc[4][4];
; #pragma unroll
;                     for (int e4 = 0; e4 < 4; ++e4) {
;                         const int e = 4 * hb + e4;
;                         float xv[11];
; #pragma unroll
;                         for (int i = 0; i < 11; ++i) { const unsigned wd = raw[i][e >> 1]; xv[i] = (e & 1) ? bfhi(wd) : bflo(wd); }
;                         const float w0 = wv[0][e4], w1 = wv[1][e4], w2 = wv[2][e4], w3 = wv[3][e4], bb = bvv[e4];
;                         float o[8];
; #pragma unroll
;                         for (int j = 0; j < 8; ++j) o[j] = silu_f(bb + w0 * xv[j] + w1 * xv[j + 1] + w2 * xv[j + 2] + w3 * xv[j + 3]);
; #pragma unroll
;                         for (int j2 = 0; j2 < 4; ++j2) pc[e4][j2] = pk2(o[2 * j2], o[2 * j2 + 1]);
;                         if (role == 0) {
;                             *(u32x4*)(Xt + (8 * lane + e) * 72 + 8 * (wave ^ (lane & 7))) = (u32x4){pc[e4][0], pc[e4][1], pc[e4][2], pc[e4][3]};
;                             *(u32x4*)(Xwt + (8 * lane + e) * 72 + 8 * (wave ^ (lane & 7))) = (u32x4){pk2(o[0] * win8[0], o[1] * win8[1]), pk2(o[2] * win8[2], o[3] * win8[3]), pk2(o[4] * win8[4], o[5] * win8[5]), pk2(o[6] * win8[6], o[7] * win8[7])};
.LBB0_435:
	v_lshlrev_b32_e32 v121, 16, v94
	s_waitcnt vmcnt(0)
	v_lshlrev_b32_e32 v120, 16, v102
	v_lshlrev_b32_e32 v125, 16, v106
	v_lshlrev_b32_e32 v124, 16, v78
	v_lshlrev_b32_e32 v198, 16, v74
	v_lshlrev_b32_e32 v199, 16, v82
	v_lshlrev_b32_e32 v201, 16, v70
	v_lshlrev_b32_e32 v200, 16, v66
	v_pk_mov_b32 v[210:211], v[120:121], v[130:131] op_sel:[1,0]
	v_pk_mov_b32 v[212:213], v[198:199], v[124:125] op_sel:[1,0]
	v_pk_mov_b32 v[214:215], v[200:201], v[198:199] op_sel:[1,0]
	v_pk_mov_b32 v[216:217], v[124:125], v[120:121] op_sel:[1,0]
	v_and_b32_e32 v0, 0x3fffffc0, v209
	v_cndmask_b32_e64 v0, 0, v0, s[12:13]
	v_lshl_add_u32 v90, v0, 2, s56
	ds_read_b128 v[114:117], v90
	ds_read_b128 v[110:113], v90 offset:16
	v_bitop3_b32 v88, v168, s67, 7 bitop3:0x6c
	s_add_i32 s44, 0, 0x12000
	v_lshlrev_b32_e32 v88, 4, v88
	v_add_u32_e32 v86, 0xffffff00, v209
	v_add_u32_e32 v0, s44, v88
	s_waitcnt vmcnt(2)
	v_pk_fma_f32 v[218:219], v[136:137], v[124:125], v[144:145] op_sel_hi:[0,1,0]
	v_pk_fma_f32 v[220:221], v[136:137], v[198:199], v[144:145] op_sel_hi:[0,1,0]
	v_pk_fma_f32 v[200:201], v[136:137], v[200:201], v[144:145] op_sel_hi:[0,1,0]
	v_pk_fma_f32 v[222:223], v[136:137], v[120:121], v[144:145] op_sel_hi:[0,1,0]
	v_pk_fma_f32 v[200:201], v[132:133], v[214:215], v[200:201] op_sel_hi:[0,1,1]
	v_pk_fma_f32 v[214:215], v[132:133], v[212:213], v[220:221] op_sel_hi:[0,1,1]
	v_pk_fma_f32 v[218:219], v[132:133], v[216:217], v[218:219] op_sel_hi:[0,1,1]
	v_pk_fma_f32 v[220:221], v[132:133], v[210:211], v[222:223] op_sel_hi:[0,1,1]
	s_waitcnt vmcnt(1)
	v_pk_fma_f32 v[198:199], v[140:141], v[198:199], v[200:201] op_sel_hi:[0,1,1]
	v_pk_fma_f32 v[124:125], v[140:141], v[124:125], v[214:215] op_sel_hi:[0,1,1]
	v_pk_fma_f32 v[120:121], v[140:141], v[120:121], v[218:219] op_sel_hi:[0,1,1]
	v_pk_fma_f32 v[130:131], v[140:141], v[130:131], v[220:221] op_sel_hi:[0,1,1]
	s_waitcnt vmcnt(0)
	v_pk_fma_f32 v[198:199], v[148:149], v[212:213], v[198:199] op_sel_hi:[0,1,1]
	v_pk_fma_f32 v[124:125], v[148:149], v[216:217], v[124:125] op_sel_hi:[0,1,1]
	v_pk_fma_f32 v[210:211], v[148:149], v[210:211], v[120:121] op_sel_hi:[0,1,1]
	v_pk_fma_f32 v[128:129], v[148:149], v[128:129], v[130:131] op_sel_hi:[0,1,1]
	v_mul_f32_e32 v90, 0xbfb8aa3b, v198
	v_mul_f32_e32 v92, 0xbfb8aa3b, v199
	v_mul_f32_e32 v98, 0xbfb8aa3b, v124
	v_mul_f32_e32 v100, 0xbfb8aa3b, v125
	v_mul_f32_e32 v118, 0xbfb8aa3b, v210
	v_mul_f32_e32 v120, 0xbfb8aa3b, v211
	v_mul_f32_e32 v121, 0xbfb8aa3b, v128
	v_mul_f32_e32 v122, 0xbfb8aa3b, v129
	v_exp_f32_e32 v90, v90
	v_exp_f32_e32 v92, v92
	v_exp_f32_e32 v98, v98
	v_exp_f32_e32 v100, v100
	v_exp_f32_e32 v118, v118
	v_exp_f32_e32 v120, v120
	v_exp_f32_e32 v121, v121
	v_exp_f32_e32 v122, v122
	v_add_f32_e32 v90, 1.0, v90
	v_add_f32_e32 v92, 1.0, v92
	v_add_f32_e32 v98, 1.0, v98
	v_add_f32_e32 v100, 1.0, v100
	v_add_f32_e32 v118, 1.0, v118
	v_add_f32_e32 v126, 1.0, v120
	v_add_f32_e32 v156, 1.0, v121
	v_add_f32_e32 v122, 1.0, v122
	v_rcp_f32_e32 v120, v90
	v_rcp_f32_e32 v121, v92
	v_rcp_f32_e32 v130, v98
	v_rcp_f32_e32 v131, v100
	v_rcp_f32_e32 v212, v118
	v_rcp_f32_e32 v213, v126
	v_rcp_f32_e32 v214, v156
	v_rcp_f32_e32 v215, v122
	v_pk_mul_f32 v[200:201], v[198:199], v[120:121]
	v_pk_mul_f32 v[120:121], v[124:125], v[130:131]
	v_pk_mul_f32 v[124:125], v[210:211], v[212:213]
	v_pk_mul_f32 v[198:199], v[128:129], v[214:215]
	v_cvt_pk_bf16_f32 v128, v200, v201
	v_cvt_pk_bf16_f32 v129, v120, v121
	v_cvt_pk_bf16_f32 v130, v124, v125
	v_cvt_pk_bf16_f32 v131, v198, v199
	s_and_saveexec_b64 s[14:15], s[10:11]
	s_xor_b64 s[14:15], exec, s[14:15]
	s_cbranch_execz .LBB0_439
	s_and_saveexec_b64 s[16:17], s[8:9]
	v_mad_u64_u32 v[120:121], vcc, v86, s46, v[0:1]
	ds_write_b128 v120, v[128:131]
	s_or_b64 exec, exec, s[16:17]
